# v80 with the s=3 wave-units-first group chosen by bit 3 of the workgroup id (mixes within each XCD so every XCD memory link carries streaming traffic)
# speedup vs baseline: 1.0003x; 1.0003x over previous
.LBB0_67:
	v_readlane_b32 s2, v255, 42
	s_nop 3
	s_cmp_lg_u32 s2, 0
	s_cbranch_scc1 .Lsw3_go
	v_readlane_b32 s3, v255, 16
	s_nop 3
	s_bitcmp1_b32 s3, 3
	s_cbranch_scc0 .Lsw3_go
	s_mov_b32 s2, 1
	s_nop 3
	v_writelane_b32 v255, s2, 42
	v_writelane_b32 v255, s30, 43
	v_writelane_b32 v255, s31, 44
	v_writelane_b32 v255, s50, 41
	s_nop 1
	s_branch .LBB0_112
